# mixb work queue: next item claimed at the start of the current item (atomic round trip overlaps the item)
# baseline (speedup 1.0000x reference)
.LBB0_409:
	s_and_saveexec_b64 s[98:99], s[4:5]
	v_mov_b32_e32 v254, 1
	global_atomic_add v254, v111, v254, s[2:3] sc0
	s_mov_b64 exec, s[98:99]
	s_cmpk_gt_i32 s24, 0x5ff
	s_mov_b64 s[6:7], -1
	s_cbranch_scc0 .LBB0_413
	s_add_i32 s6, s24, 0xfffffa00
	s_lshr_b32 s8, s6, 5
	s_lshr_b32 s7, s24, 1
	s_bfe_u32 s6, s24, 0x40001
	s_lshl_b64 s[20:21], s[8:9], 17
	s_add_u32 s22, s34, s20
	s_addc_u32 s23, s35, s21
	s_bfe_u32 s7, s7, 0x20002
	s_lshl_b32 s25, s7, 7
	s_add_u32 s22, s22, s25
	s_addc_u32 s23, s23, 0
	s_add_u32 s20, s46, s20
	s_addc_u32 s21, s47, s21
	s_lshl_b32 s7, s7, 15
	s_add_u32 s20, s20, s7
	s_addc_u32 s21, s21, 0
	s_lshl_b32 s7, s24, 7
	s_and_b32 s7, s7, 0x80
	v_or_b32_e32 v2, s7, v1
	v_lshl_or_b32 v166, s8, 8, v2
	v_mov_b32_e32 v167, v111
	v_lshlrev_b64 v[2:3], 11, v[166:167]
	v_lshl_add_u64 v[2:3], s[12:13], 0, v[2:3]
	s_lshl_b32 s8, s6, 7
	v_lshl_add_u64 v[2:3], v[2:3], 0, s[8:9]
	v_lshlrev_b32_e32 v4, 1, v108
	v_mov_b32_e32 v5, v111
	v_lshl_add_u64 v[2:3], v[2:3], 0, v[4:5]
	v_mov_b32_e32 v151, v111
	s_waitcnt vmcnt(4)
	v_lshl_add_u64 v[10:11], v[2:3], 0, v[150:151]
	v_mov_b32_e32 v153, v111
	s_waitcnt vmcnt(2)
	v_add_co_u32_e32 v14, vcc, s48, v10
	v_lshl_add_u64 v[34:35], s[22:23], 0, v[152:153]
	v_mov_b32_e32 v155, v111
	v_addc_co_u32_e32 v15, vcc, 0, v11, vcc
	s_waitcnt vmcnt(3)
	v_lshl_add_u64 v[42:43], v[34:35], 0, v[154:155]
	s_waitcnt vmcnt(1)
	v_lshl_add_u64 v[50:51], v[34:35], 0, v[112:113]
	v_lshl_add_u64 v[22:23], v[34:35], 0, v[114:115]
	v_add_co_u32_e32 v34, vcc, s48, v42
	v_mov_b32_e32 v157, v111
	s_nop 0
	v_addc_co_u32_e32 v35, vcc, 0, v43, vcc
	v_lshl_add_u64 v[26:27], s[20:21], 0, v[152:153]
	v_lshl_add_u64 v[36:37], s[20:21], 0, v[154:155]
	v_add_co_u32_e32 v42, vcc, s49, v42
	v_lshl_add_u64 v[44:45], s[20:21], 0, v[156:157]
	v_lshl_add_u64 v[168:169], v[26:27], 0, v[154:155]
	v_lshl_add_u64 v[38:39], v[36:37], 0, v[152:153]
	v_addc_co_u32_e32 v43, vcc, 0, v43, vcc
	v_lshl_add_u64 v[46:47], v[44:45], 0, v[152:153]
	global_load_dwordx4 v[2:5], v[10:11], off
	global_load_dwordx4 v[6:9], v[10:11], off offset:64
	s_nop 0
	global_load_dwordx4 v[10:13], v[14:15], off
	s_nop 0
	global_load_dwordx4 v[14:17], v[14:15], off offset:64
	s_nop 0
	global_load_dwordx4 v[18:21], v[50:51], off
	s_nop 0
	global_load_dwordx4 v[22:25], v[22:23], off
	v_lshl_add_u64 v[170:171], v[26:27], 0, v[156:157]
	global_load_dwordx4 v[26:29], v[168:169], off
	global_load_dwordx4 v[30:33], v[170:171], off
	s_barrier
	global_load_dwordx4 v[34:37], v[34:35], off
	s_nop 0
	global_load_dwordx4 v[38:41], v[38:39], off offset:128
	s_nop 0
	global_load_dwordx4 v[42:45], v[42:43], off
	s_nop 0
	global_load_dwordx4 v[46:49], v[46:47], off offset:128
	s_lshl_b32 s6, s6, 6
	s_mov_b32 s7, 2
	s_waitcnt vmcnt(7)
	ds_write_b128 v107, v[18:21]
	s_waitcnt vmcnt(6)
	ds_write_b128 v107, v[22:25] offset:4608
	s_waitcnt vmcnt(5)
	ds_write_b128 v107, v[26:29] offset:9216
	s_waitcnt vmcnt(4)
	ds_write_b128 v107, v[30:33] offset:13824
	s_waitcnt lgkmcnt(0)
	s_barrier
	s_waitcnt vmcnt(3)
	ds_write_b128 v107, v[34:37] offset:18432
	s_waitcnt vmcnt(2)
	ds_write_b128 v107, v[38:41] offset:27648
	s_waitcnt vmcnt(1)
	ds_write_b128 v107, v[42:45] offset:23040
	s_waitcnt vmcnt(0)
	ds_write_b128 v107, v[46:49] offset:32256
	ds_read_b128 v[18:21], v188
	ds_read_b128 v[22:25], v188 offset:64
	ds_read_b128 v[30:33], v188 offset:2304
	ds_read_b128 v[34:37], v188 offset:2368
	s_waitcnt lgkmcnt(3)
	v_mfma_f32_16x16x32_bf16 v[26:29], v[18:21], v[2:5], 0
	ds_read_b128 v[42:45], v188 offset:4608
	ds_read_b128 v[46:49], v188 offset:4672
	ds_read_b128 v[56:59], v188 offset:6912
	ds_read_b128 v[60:63], v188 offset:6976
	v_mfma_f32_16x16x32_bf16 v[18:21], v[18:21], v[10:13], 0
	s_waitcnt lgkmcnt(5)
	v_mfma_f32_16x16x32_bf16 v[38:41], v[30:33], v[2:5], 0
	v_mfma_f32_16x16x32_bf16 v[30:33], v[30:33], v[10:13], 0
	s_waitcnt lgkmcnt(3)
	v_mfma_f32_16x16x32_bf16 v[52:55], v[42:45], v[2:5], 0
	v_mfma_f32_16x16x32_bf16 v[26:29], v[22:25], v[6:9], v[26:29]
	v_mfma_f32_16x16x32_bf16 v[18:21], v[22:25], v[14:17], v[18:21]
	v_mfma_f32_16x16x32_bf16 v[22:25], v[34:37], v[6:9], v[38:41]
	v_mfma_f32_16x16x32_bf16 v[34:37], v[34:37], v[14:17], v[30:33]
	s_nop 4
	v_mul_f32_e32 v38, 0x3fb8aa3b, v28
	v_mul_f32_e32 v39, 0x3fb8aa3b, v29
	v_and_b32_e32 v31, 64, v195
	v_xor_b32_e32 v30, 16, v195
	v_add_u32_e32 v31, 64, v31
	v_mfma_f32_16x16x32_bf16 v[42:45], v[42:45], v[10:13], 0
	v_cmp_lt_i32_e32 vcc, v30, v31
	v_mul_f32_e32 v33, 0x3fb8aa3b, v27
	v_xor_b32_e32 v32, 32, v195
	s_waitcnt lgkmcnt(1)
	v_mfma_f32_16x16x32_bf16 v[64:67], v[56:59], v[2:5], 0
	v_cndmask_b32_e32 v30, v195, v30, vcc
	v_lshlrev_b32_e32 v151, 2, v30
	v_mul_f32_e32 v30, 0x3fb8aa3b, v26
	v_mfma_f32_16x16x32_bf16 v[68:71], v[46:49], v[6:9], v[52:55]
	v_max3_f32 v30, v30, s53, v33
	v_max3_f32 v30, v30, v38, v39
	v_cmp_lt_i32_e32 vcc, v32, v31
	v_mfma_f32_16x16x32_bf16 v[40:43], v[46:49], v[14:17], v[42:45]
	v_mul_f32_e32 v48, 0x3fb8aa3b, v22
	v_mul_f32_e32 v49, 0x3fb8aa3b, v23
	v_mul_f32_e32 v52, 0x3fb8aa3b, v24
	s_waitcnt lgkmcnt(0)
	v_mfma_f32_16x16x32_bf16 v[44:47], v[60:63], v[6:9], v[64:67]
	v_mul_f32_e32 v53, 0x3fb8aa3b, v25
	v_max3_f32 v30, v30, v48, v49
	v_mul_f32_e32 v54, 0x3fb8aa3b, v68
	v_max3_f32 v30, v30, v52, v53
	v_mul_f32_e32 v33, 0x3fb8aa3b, v69
	v_max3_f32 v30, v30, v54, v33
	v_mul_f32_e32 v33, 0x3fb8aa3b, v70
	v_mul_f32_e32 v38, 0x3fb8aa3b, v71
	v_max3_f32 v30, v30, v33, v38
	v_mul_f32_e32 v33, 0x3fb8aa3b, v44
	v_mul_f32_e32 v38, 0x3fb8aa3b, v45
	v_max3_f32 v30, v30, v33, v38
	v_mul_f32_e32 v33, 0x3fb8aa3b, v46
	v_mul_f32_e32 v38, 0x3fb8aa3b, v47
	v_max3_f32 v38, v30, v33, v38
	ds_bpermute_b32 v39, v151, v38
	v_cndmask_b32_e32 v30, v195, v32, vcc
	v_lshlrev_b32_e32 v153, 2, v30
	v_mfma_f32_16x16x32_bf16 v[30:33], v[56:59], v[10:13], 0
	s_waitcnt lgkmcnt(0)
	v_max_f32_e32 v39, v39, v39
	v_max_f32_e32 v38, v38, v39
	ds_bpermute_b32 v39, v153, v38
	v_mfma_f32_16x16x32_bf16 v[72:75], v[60:63], v[14:17], v[30:33]
	s_waitcnt lgkmcnt(0)
	v_max3_f32 v155, v38, v39, s53
	v_fma_f32 v22, v22, s52, -v155
	v_exp_f32_e32 v60, v22
	v_fma_f32 v22, v23, s52, -v155
	v_exp_f32_e32 v64, v22
	v_fma_f32 v22, v24, s52, -v155
	v_exp_f32_e32 v54, v22
	v_fma_f32 v22, v25, s52, -v155
	v_exp_f32_e32 v58, v22
	v_fma_f32 v22, v68, s52, -v155
	v_exp_f32_e32 v62, v22
	v_fma_f32 v22, v69, s52, -v155
	v_exp_f32_e32 v66, v22
	v_fma_f32 v22, v70, s52, -v155
	v_exp_f32_e32 v68, v22
	v_fma_f32 v22, v71, s52, -v155
	v_exp_f32_e32 v70, v22
	v_mul_f32_e32 v22, 0x3fb8aa3b, v18
	v_mul_f32_e32 v23, 0x3fb8aa3b, v19
	v_max3_f32 v22, v22, s53, v23
	v_mul_f32_e32 v23, 0x3fb8aa3b, v20
	v_mul_f32_e32 v24, 0x3fb8aa3b, v21
	v_max3_f32 v22, v22, v23, v24
	v_mul_f32_e32 v23, 0x3fb8aa3b, v34
	v_mul_f32_e32 v24, 0x3fb8aa3b, v35
	v_max3_f32 v22, v22, v23, v24
	v_mul_f32_e32 v23, 0x3fb8aa3b, v36
	v_mul_f32_e32 v24, 0x3fb8aa3b, v37
	v_max3_f32 v22, v22, v23, v24
	v_mul_f32_e32 v23, 0x3fb8aa3b, v40
	v_mul_f32_e32 v24, 0x3fb8aa3b, v41
	v_max3_f32 v22, v22, v23, v24
	v_mul_f32_e32 v23, 0x3fb8aa3b, v42
	v_mul_f32_e32 v24, 0x3fb8aa3b, v43
	v_max3_f32 v22, v22, v23, v24
	v_mul_f32_e32 v23, 0x3fb8aa3b, v72
	v_mul_f32_e32 v24, 0x3fb8aa3b, v73
	v_max3_f32 v22, v22, v23, v24
	v_mul_f32_e32 v23, 0x3fb8aa3b, v74
	v_mul_f32_e32 v24, 0x3fb8aa3b, v75
	v_max3_f32 v22, v22, v23, v24
	ds_bpermute_b32 v23, v151, v22
	v_sub_f32_e32 v30, 0xf149f2ca, v155
	v_fma_f32 v26, v26, s52, -v155
	v_exp_f32_e32 v52, v30
	v_exp_f32_e32 v30, v26
	s_waitcnt lgkmcnt(0)
	v_max_f32_e32 v23, v23, v23
	v_max_f32_e32 v22, v22, v23
	ds_bpermute_b32 v23, v153, v22
	v_fma_f32 v26, v27, s52, -v155
	v_fma_f32 v24, v44, s52, -v155
	v_exp_f32_e32 v32, v26
	v_fma_f32 v26, v28, s52, -v155
	s_waitcnt lgkmcnt(0)
	v_max3_f32 v157, v22, v23, s53
	v_fma_f32 v18, v18, s52, -v157
	v_exp_f32_e32 v31, v18
	v_fma_f32 v18, v19, s52, -v157
	v_exp_f32_e32 v33, v18
	v_fma_f32 v18, v20, s52, -v157
	v_exp_f32_e32 v39, v18
	v_fma_f32 v18, v21, s52, -v157
	v_exp_f32_e32 v57, v18
	v_fma_f32 v18, v34, s52, -v157
	v_exp_f32_e32 v61, v18
	v_fma_f32 v18, v35, s52, -v157
	v_exp_f32_e32 v65, v18
	v_fma_f32 v18, v36, s52, -v157
	v_exp_f32_e32 v55, v18
	v_fma_f32 v18, v37, s52, -v157
	v_exp_f32_e32 v59, v18
	v_fma_f32 v18, v40, s52, -v157
	v_exp_f32_e32 v63, v18
	v_fma_f32 v18, v41, s52, -v157
	v_exp_f32_e32 v67, v18
	v_fma_f32 v18, v42, s52, -v157
	v_exp_f32_e32 v69, v18
	v_fma_f32 v18, v43, s52, -v157
	v_exp_f32_e32 v71, v18
	v_fma_f32 v18, v72, s52, -v157
	v_exp_f32_e32 v176, v24
	v_fma_f32 v24, v45, s52, -v155
	v_sub_f32_e32 v22, 0xf149f2ca, v157
	v_exp_f32_e32 v177, v18
	v_fma_f32 v18, v73, s52, -v157
	v_exp_f32_e32 v38, v26
	v_fma_f32 v26, v29, s52, -v155
	v_exp_f32_e32 v180, v24
	v_fma_f32 v24, v46, s52, -v155
	v_exp_f32_e32 v53, v22
	v_exp_f32_e32 v181, v18
	v_fma_f32 v18, v74, s52, -v157
	v_exp_f32_e32 v56, v26
	v_exp_f32_e32 v184, v24
	v_fma_f32 v24, v47, s52, -v155
	v_exp_f32_e32 v185, v18
	v_fma_f32 v18, v75, s52, -v157
	v_add_u32_e32 v22, 0x2000, v109
	v_exp_f32_e32 v212, v24
	v_exp_f32_e32 v213, v18
	ds_read2_b64 v[18:21], v22 offset0:128 offset1:132
	ds_read2_b64 v[22:25], v22 offset0:136 offset1:140
	v_pk_mul_f32 v[86:87], v[52:53], 0 op_sel_hi:[1,0]
	v_cvt_pk_bf16_f32 v78, v30, v32
	v_cvt_pk_bf16_f32 v79, v38, v56
	v_cvt_pk_bf16_f32 v80, v60, v64
	v_cvt_pk_bf16_f32 v82, v31, v33
	v_cvt_pk_bf16_f32 v83, v39, v57
	v_cvt_pk_bf16_f32 v84, v61, v65
	v_mov_b32_e32 v90, v86
	v_mov_b32_e32 v91, v86
	v_mov_b32_e32 v92, v86
	v_mov_b32_e32 v93, v86
	v_cvt_pk_bf16_f32 v81, v54, v58
	v_mov_b32_e32 v86, v87
	v_mov_b32_e32 v88, v87
	v_mov_b32_e32 v89, v87
	v_cvt_pk_bf16_f32 v85, v55, v59
	s_waitcnt lgkmcnt(1)
	v_mfma_f32_16x16x32_bf16 v[26:29], v[18:21], v[78:81], v[90:93]
	v_add_u32_e32 v34, 0x2800, v109
	v_cvt_pk_bf16_f32 v172, v62, v66
	v_cvt_pk_bf16_f32 v173, v68, v70
	v_mfma_f32_16x16x32_bf16 v[18:21], v[18:21], v[82:85], v[86:89]
	v_cvt_pk_bf16_f32 v174, v176, v180
	v_cvt_pk_bf16_f32 v175, v184, v212
	v_cvt_pk_bf16_f32 v196, v63, v67
	v_cvt_pk_bf16_f32 v197, v69, v71
	v_cvt_pk_bf16_f32 v198, v177, v181
	v_cvt_pk_bf16_f32 v199, v185, v213
	s_waitcnt lgkmcnt(0)
	v_mfma_f32_16x16x32_bf16 v[42:45], v[22:25], v[172:175], v[26:29]
	v_add_u32_e32 v40, 0x3000, v109
	ds_read2_b64 v[200:203], v40 offset0:192 offset1:196
	v_pk_add_f32 v[30:31], v[30:31], 0 op_sel_hi:[1,0]
	v_mfma_f32_16x16x32_bf16 v[18:21], v[22:25], v[196:199], v[18:21]
	ds_read2_b64 v[22:25], v34 offset0:160 offset1:164
	ds_read2_b64 v[34:37], v34 offset0:168 offset1:172
	v_pk_add_f32 v[30:31], v[32:33], v[30:31]
	s_waitcnt lgkmcnt(1)
	v_mfma_f32_16x16x32_bf16 v[26:29], v[22:25], v[78:81], v[90:93]
	v_add_f32_e64 v30, v38, v30
	v_add_f32_e64 v31, v39, v31
	v_pk_add_f32 v[30:31], v[56:57], v[30:31]
	s_waitcnt lgkmcnt(0)
	v_mfma_f32_16x16x32_bf16 v[46:49], v[34:37], v[172:175], v[26:29]
	v_add_f32_e64 v30, v60, v30
	v_add_f32_e64 v31, v61, v31
	v_pk_add_f32 v[56:57], v[64:65], v[30:31]
	v_add_co_u32_e32 v26, vcc, s50, v50
	v_mfma_f32_16x16x32_bf16 v[22:25], v[22:25], v[82:85], v[86:89]
	s_nop 0
	v_addc_co_u32_e32 v27, vcc, 0, v51, vcc
	v_add_co_u32_e32 v28, vcc, s51, v50
	v_mfma_f32_16x16x32_bf16 v[22:25], v[34:37], v[196:199], v[22:25]
	s_nop 0
	v_addc_co_u32_e32 v29, vcc, 0, v51, vcc
	global_load_dwordx4 v[94:97], v[26:27], off
	global_load_dwordx4 v[98:101], v[28:29], off
	global_load_dwordx4 v[102:105], v[168:169], off offset:256
	global_load_dwordx4 v[74:77], v[170:171], off offset:256
	ds_read2_b64 v[204:207], v40 offset0:200 offset1:204
	v_add_u32_e32 v40, 0x3800, v109
	v_mfma_f32_16x16x32_bf16 v[26:29], v[200:203], v[78:81], v[90:93]
	ds_read2_b64 v[208:211], v40 offset0:224 offset1:228
	v_pk_add_f32 v[54:55], v[54:55], v[56:57]
	v_mfma_f32_16x16x32_bf16 v[200:203], v[200:203], v[82:85], v[86:89]
	v_add_f32_e64 v54, v58, v54
	v_add_f32_e64 v55, v59, v55
	v_pk_add_f32 v[54:55], v[62:63], v[54:55]
	s_waitcnt lgkmcnt(1)
	v_mfma_f32_16x16x32_bf16 v[34:37], v[204:207], v[172:175], v[26:29]
	v_add_f32_e64 v54, v66, v54
	v_add_f32_e64 v55, v67, v55
	v_pk_add_f32 v[54:55], v[68:69], v[54:55]
	v_mfma_f32_16x16x32_bf16 v[26:29], v[204:207], v[196:199], v[200:203]
	v_add_f32_e64 v54, v70, v54
	v_add_f32_e64 v55, v71, v55
	v_pk_add_f32 v[54:55], v[176:177], v[54:55]
	ds_read2_b64 v[200:203], v40 offset0:232 offset1:236
	s_waitcnt lgkmcnt(1)
	v_mfma_f32_16x16x32_bf16 v[78:81], v[208:211], v[78:81], v[90:93]
	v_add_f32_e64 v54, v180, v54
	v_add_f32_e64 v55, v181, v55
	v_lshl_add_u64 v[176:177], v[50:51], 0, s[18:19]
	v_pk_add_f32 v[54:55], v[184:185], v[54:55]
	v_mfma_f32_16x16x32_bf16 v[82:85], v[208:211], v[82:85], v[86:89]
	v_add_f32_e64 v54, v212, v54
	v_add_f32_e64 v55, v213, v55
	s_waitcnt lgkmcnt(0)
	s_barrier
	v_mfma_f32_16x16x32_bf16 v[38:41], v[200:203], v[172:175], v[78:81]
	v_fma_f32 v172, v52, 0, v54
	v_fma_f32 v173, v53, 0, v55
	v_lshl_add_u64 v[174:175], v[50:51], 0, s[16:17]
	v_mfma_f32_16x16x32_bf16 v[30:33], v[200:203], v[196:199], v[82:85]

.LBB0_421:
	s_cmp_lt_i32 s56, -3
	s_cbranch_scc1 .LBB0_430
	s_cmp_eq_u32 s27, 0
	s_cselect_b64 s[24:25], -1, 0
	s_lshr_b32 s20, s26, 6
	s_lshl_b32 s29, s28, 8
	s_lshl_b32 s26, s28, 1
	s_and_b64 s[6:7], s[24:25], exec
	s_cselect_b32 s6, s54, 0x18d24000
	s_add_u32 s59, s42, s6
	s_addc_u32 s60, s43, 0
	s_and_b64 s[6:7], s[24:25], exec
	s_cselect_b32 s6, 0, s57
	s_add_i32 s6, s20, s6
	s_mov_b32 s7, s9
	s_lshl_b64 s[30:31], s[6:7], 10
	s_or_b32 s30, s30, s29
	s_or_b64 s[30:31], s[30:31], s[8:9]
	s_lshl_b64 s[30:31], s[30:31], 7
	s_lshl_b32 s6, s6, 3
	s_or_b32 s26, s26, s27
	v_lshl_add_u64 v[34:35], v[136:137], 0, s[30:31]
	v_mov_b32_e32 v159, v111
	s_or_b32 s6, s26, s6
	v_lshl_add_u64 v[36:37], v[34:35], 0, v[110:111]
	v_lshl_add_u64 v[34:35], v[34:35], 0, v[158:159]
	s_lshl_b64 s[6:7], s[6:7], 14
	global_load_dwordx4 v[58:61], v[36:37], off
	global_load_dwordx4 v[62:65], v[34:35], off
	v_lshl_add_u64 v[34:35], v[138:139], 0, s[6:7]
	v_mov_b32_e32 v161, v111
	v_lshl_add_u64 v[36:37], v[34:35], 0, v[160:161]
	v_mov_b32_e32 v163, v111
	s_waitcnt vmcnt(6)
	v_lshl_add_u64 v[38:39], v[34:35], 0, v[162:163]
	global_load_dwordx4 v[78:81], v[36:37], off
	global_load_dwordx4 v[74:77], v[38:39], off
	v_lshl_add_u64 v[36:37], v[34:35], 0, v[110:111]
	v_lshl_add_u64 v[34:35], v[34:35], 0, v[158:159]
	global_load_dwordx4 v[70:73], v[36:37], off
	global_load_dwordx4 v[66:69], v[34:35], off
	s_lshl_b32 s6, s28, 9
	s_add_u32 s6, s59, s6
	s_addc_u32 s7, s60, 0
	s_lshl_b32 s28, s8, 1
	s_add_u32 s6, s6, s28
	s_addc_u32 s7, s7, 0
	v_lshlrev_b32_e32 v34, 1, v116
	v_mov_b32_e32 v35, v111
	v_lshl_add_u64 v[166:167], s[6:7], 0, v[34:35]
	s_or_b32 s6, s8, s29
	s_mov_b32 s58, 0
	s_mov_b32 s27, s9
	s_add_i32 s59, s56, 3
	s_add_i32 s60, s56, 4
	s_lshl_b32 s61, s6, 7
	s_mov_b32 s62, s57
	s_and_b64 s[98:99], s[24:25], exec
	s_cselect_b32 s98, 0, s62
	s_add_i32 s98, s98, s20
	s_ashr_i32 s99, s98, 31
	s_lshl_b64 s[98:99], s[98:99], 3
	s_or_b64 s[98:99], s[98:99], s[26:27]
	s_lshl_b64 s[100:101], s[98:99], 9
	v_lshl_add_u64 v[82:83], v[144:145], 0, s[100:101]
	global_load_dword v250, v[82:83], off
	global_load_dword v251, v[82:83], off offset:64
	global_load_dword v252, v[82:83], off offset:128
	global_load_dword v253, v[82:83], off offset:192
	global_load_dword v155, v[82:83], off offset:256
	global_load_dword v186, v[82:83], off offset:320
	global_load_dword v151, v[82:83], off offset:384
	global_load_dword v153, v[82:83], off offset:448
	s_cmp_gt_i32 s56, 0
	s_cbranch_scc1 .Lscpf_l0_pre
	s_lshl_b64 s[100:101], s[98:99], 14
	v_lshl_add_u64 v[236:237], v[140:141], 0, s[100:101]
	global_load_dwordx4 v[224:227], v[236:237], off
	global_load_dwordx4 v[228:231], v[236:237], off offset:64
	global_load_dwordx4 v[232:235], v[236:237], off offset:128
	s_nop 0
	global_load_dwordx4 v[236:239], v[236:237], off offset:192
	s_lshl_b64 s[100:101], s[98:99], 13
	v_lshl_add_u64 v[244:245], v[142:143], 0, s[100:101]
	global_load_dwordx4 v[240:243], v[244:245], off
	s_nop 0
	global_load_dwordx4 v[244:247], v[244:245], off offset:64

.Lscpf_l0_wd:
	v_mov_b32_e32 v182, v250
	v_mov_b32_e32 v180, v251
	v_mov_b32_e32 v178, v252
	v_mov_b32_e32 v176, v253
	v_mov_b32_e32 v174, v155
	v_mov_b32_e32 v172, v186
	v_mov_b32_e32 v170, v151
	v_mov_b32_e32 v168, v153
	s_cmp_lt_i32 s58, s56
	s_cbranch_scc1 .Lscpf_l0_nq
	v_mov_b32_e32 v38, v224
	v_mov_b32_e32 v39, v225
	v_mov_b32_e32 v40, v226
	v_mov_b32_e32 v41, v227
	v_mov_b32_e32 v34, v228
	v_mov_b32_e32 v35, v229
	v_mov_b32_e32 v36, v230
	v_mov_b32_e32 v37, v231
	v_mov_b32_e32 v42, v232
	v_mov_b32_e32 v43, v233
	v_mov_b32_e32 v44, v234
	v_mov_b32_e32 v45, v235
	v_mov_b32_e32 v46, v236
	v_mov_b32_e32 v47, v237
	v_mov_b32_e32 v48, v238
	v_mov_b32_e32 v49, v239
	v_mov_b32_e32 v54, v240
	v_mov_b32_e32 v55, v241
	v_mov_b32_e32 v56, v242
	v_mov_b32_e32 v57, v243
	v_mov_b32_e32 v50, v244
	v_mov_b32_e32 v51, v245
	v_mov_b32_e32 v52, v246
	v_mov_b32_e32 v53, v247

.LBB0_428:
	s_add_i32 s58, s58, 1
	s_min_i32 s29, s58, s59
	s_sub_i32 s63, s57, s29
	s_and_b64 s[30:31], s[24:25], exec
	s_cselect_b32 s29, s29, s63
	s_add_i32 s30, s29, s20
	s_ashr_i32 s31, s30, 31
	s_lshl_b64 s[98:99], s[30:31], 3
	s_or_b64 s[98:99], s[98:99], s[26:27]
	s_lshl_b32 s29, s26, 14
	s_lshl_b64 s[30:31], s[30:31], 17
	s_or_b32 s64, s30, s29
	s_mov_b32 s65, s31
	v_lshl_add_u64 v[58:59], v[146:147], 0, s[64:65]
	v_add_co_u32_e32 v60, vcc, s33, v58
	s_waitcnt lgkmcnt(0)
	s_nop 0
	v_addc_co_u32_e32 v61, vcc, 0, v59, vcc
	s_barrier
	global_load_dwordx4 v[66:69], v[58:59], off
	global_load_dwordx4 v[70:73], v[60:61], off
	v_add_co_u32_e32 v60, vcc, 0x2000, v58
	s_or_b32 s30, s30, s61
	s_nop 0
	v_addc_co_u32_e32 v61, vcc, 0, v59, vcc
	v_add_co_u32_e32 v58, vcc, 0x3000, v58
	s_nop 1
	v_addc_co_u32_e32 v59, vcc, 0, v59, vcc
	global_load_dwordx4 v[74:77], v[60:61], off
	global_load_dwordx4 v[78:81], v[58:59], off
	v_lshl_add_u64 v[58:59], v[148:149], 0, s[30:31]
	v_add_co_u32_e32 v60, vcc, 0x1000, v58
	s_nop 1
	v_addc_co_u32_e32 v61, vcc, 0, v59, vcc
	global_load_dwordx4 v[62:65], v[58:59], off
	s_nop 0
	global_load_dwordx4 v[58:61], v[60:61], off
	s_cmp_gt_i32 s58, s59
	s_cbranch_scc1 .Lscpf_l0_nopf
	s_lshl_b64 s[100:101], s[98:99], 9
	v_lshl_add_u64 v[82:83], v[144:145], 0, s[100:101]
	global_load_dword v250, v[82:83], off
	global_load_dword v251, v[82:83], off offset:64
	global_load_dword v252, v[82:83], off offset:128
	global_load_dword v253, v[82:83], off offset:192
	global_load_dword v155, v[82:83], off offset:256
	global_load_dword v186, v[82:83], off offset:320
	global_load_dword v151, v[82:83], off offset:384
	global_load_dword v153, v[82:83], off offset:448
	s_cmp_lt_i32 s58, s56
	s_cbranch_scc1 .Lscpf_l0_nopf
	s_lshl_b64 s[100:101], s[98:99], 14
	v_lshl_add_u64 v[236:237], v[140:141], 0, s[100:101]
	global_load_dwordx4 v[224:227], v[236:237], off
	global_load_dwordx4 v[228:231], v[236:237], off offset:64
	global_load_dwordx4 v[232:235], v[236:237], off offset:128
	s_nop 0
	global_load_dwordx4 v[236:239], v[236:237], off offset:192
	s_lshl_b64 s[100:101], s[98:99], 13
	v_lshl_add_u64 v[244:245], v[142:143], 0, s[100:101]
	global_load_dwordx4 v[240:243], v[244:245], off
	s_nop 0
	global_load_dwordx4 v[244:247], v[244:245], off offset:64

.LBB0_432:
	s_barrier
	s_and_saveexec_b64 s[6:7], s[4:5]
	s_cbranch_execz .LBB0_408
	s_load_dword s8, s[10:11], 0x0
	s_mov_b64 s[20:21], exec
	s_waitcnt vmcnt(7)
	v_mbcnt_lo_u32_b32 v2, s20, 0
	v_mbcnt_hi_u32_b32 v2, s21, v2
	v_cmp_eq_u32_e32 vcc, 0, v2
	s_and_saveexec_b64 s[22:23], vcc
	s_cbranch_execz .LBB0_407
	s_waitcnt vmcnt(0)
	v_mov_b32_e32 v3, v254
	s_branch .LBB0_407

.LBB0_1149:
	s_and_saveexec_b64 s[98:99], s[4:5]
	v_mov_b32_e32 v254, 1
	global_atomic_add v254, v111, v254, s[2:3] sc0
	s_mov_b64 exec, s[98:99]
	s_cmpk_gt_i32 s24, 0x5ff
	s_mov_b64 s[6:7], -1
	s_cbranch_scc0 .LBB0_1153
	s_add_i32 s6, s24, 0xfffffa00
	s_lshr_b32 s8, s6, 5
	s_lshr_b32 s7, s24, 1
	s_bfe_u32 s6, s24, 0x40001
	s_lshl_b64 s[20:21], s[8:9], 17
	s_add_u32 s22, s34, s20
	s_addc_u32 s23, s35, s21
	s_bfe_u32 s7, s7, 0x20002
	s_lshl_b32 s25, s7, 7
	s_add_u32 s22, s22, s25
	s_addc_u32 s23, s23, 0
	s_add_u32 s20, s36, s20
	s_addc_u32 s21, s37, s21
	s_lshl_b32 s7, s7, 15
	s_add_u32 s20, s20, s7
	s_addc_u32 s21, s21, 0
	s_lshl_b32 s7, s24, 7
	s_and_b32 s7, s7, 0x80
	v_or_b32_e32 v2, s7, v1
	v_lshl_or_b32 v168, s8, 8, v2
	v_mov_b32_e32 v169, v111
	v_lshlrev_b64 v[2:3], 11, v[168:169]
	v_lshl_add_u64 v[2:3], s[12:13], 0, v[2:3]
	s_lshl_b32 s8, s6, 7
	v_lshl_add_u64 v[2:3], v[2:3], 0, s[8:9]
	v_lshlrev_b32_e32 v4, 1, v108
	v_mov_b32_e32 v5, v111
	v_lshl_add_u64 v[2:3], v[2:3], 0, v[4:5]
	v_mov_b32_e32 v153, v111
	s_waitcnt vmcnt(4)
	v_lshl_add_u64 v[10:11], v[2:3], 0, v[152:153]
	v_mov_b32_e32 v155, v111
	s_waitcnt vmcnt(2)
	v_add_co_u32_e32 v14, vcc, s46, v10
	v_lshl_add_u64 v[34:35], s[22:23], 0, v[154:155]
	v_mov_b32_e32 v157, v111
	v_addc_co_u32_e32 v15, vcc, 0, v11, vcc
	v_lshl_add_u64 v[42:43], v[34:35], 0, v[156:157]
	s_waitcnt vmcnt(1)
	v_lshl_add_u64 v[50:51], v[34:35], 0, v[112:113]
	v_lshl_add_u64 v[22:23], v[34:35], 0, v[114:115]
	v_add_co_u32_e32 v34, vcc, s46, v42
	v_mov_b32_e32 v159, v111
	s_nop 0
	v_addc_co_u32_e32 v35, vcc, 0, v43, vcc
	v_lshl_add_u64 v[26:27], s[20:21], 0, v[154:155]
	v_lshl_add_u64 v[36:37], s[20:21], 0, v[156:157]
	v_add_co_u32_e32 v42, vcc, s47, v42
	v_lshl_add_u64 v[44:45], s[20:21], 0, v[158:159]
	v_lshl_add_u64 v[170:171], v[26:27], 0, v[156:157]
	v_lshl_add_u64 v[38:39], v[36:37], 0, v[154:155]
	v_addc_co_u32_e32 v43, vcc, 0, v43, vcc
	v_lshl_add_u64 v[46:47], v[44:45], 0, v[154:155]
	global_load_dwordx4 v[2:5], v[10:11], off
	global_load_dwordx4 v[6:9], v[10:11], off offset:64
	s_nop 0
	global_load_dwordx4 v[10:13], v[14:15], off
	s_nop 0
	global_load_dwordx4 v[14:17], v[14:15], off offset:64
	s_nop 0
	global_load_dwordx4 v[18:21], v[50:51], off
	s_nop 0
	global_load_dwordx4 v[22:25], v[22:23], off
	v_lshl_add_u64 v[172:173], v[26:27], 0, v[158:159]
	global_load_dwordx4 v[26:29], v[170:171], off
	global_load_dwordx4 v[30:33], v[172:173], off
	s_barrier
	global_load_dwordx4 v[34:37], v[34:35], off
	s_nop 0
	global_load_dwordx4 v[38:41], v[38:39], off offset:128
	s_nop 0
	global_load_dwordx4 v[42:45], v[42:43], off
	s_nop 0
	global_load_dwordx4 v[46:49], v[46:47], off offset:128
	s_lshl_b32 s6, s6, 6
	s_mov_b32 s7, 2
	s_waitcnt vmcnt(7)
	ds_write_b128 v107, v[18:21]
	s_waitcnt vmcnt(6)
	ds_write_b128 v107, v[22:25] offset:4608
	s_waitcnt vmcnt(5)
	ds_write_b128 v107, v[26:29] offset:9216
	s_waitcnt vmcnt(4)
	ds_write_b128 v107, v[30:33] offset:13824
	s_waitcnt lgkmcnt(0)
	s_barrier
	s_waitcnt vmcnt(3)
	ds_write_b128 v107, v[34:37] offset:18432
	s_waitcnt vmcnt(2)
	ds_write_b128 v107, v[38:41] offset:27648
	s_waitcnt vmcnt(1)
	ds_write_b128 v107, v[42:45] offset:23040
	s_waitcnt vmcnt(0)
	ds_write_b128 v107, v[46:49] offset:32256
	ds_read_b128 v[18:21], v183
	ds_read_b128 v[22:25], v183 offset:64
	ds_read_b128 v[30:33], v183 offset:2304
	ds_read_b128 v[34:37], v183 offset:2368
	s_waitcnt lgkmcnt(3)
	v_mfma_f32_16x16x32_bf16 v[26:29], v[18:21], v[2:5], 0
	ds_read_b128 v[42:45], v183 offset:4608
	ds_read_b128 v[46:49], v183 offset:4672
	ds_read_b128 v[56:59], v183 offset:6912
	ds_read_b128 v[60:63], v183 offset:6976
	v_mfma_f32_16x16x32_bf16 v[18:21], v[18:21], v[10:13], 0
	s_waitcnt lgkmcnt(5)
	v_mfma_f32_16x16x32_bf16 v[38:41], v[30:33], v[2:5], 0
	v_mfma_f32_16x16x32_bf16 v[30:33], v[30:33], v[10:13], 0
	s_waitcnt lgkmcnt(3)
	v_mfma_f32_16x16x32_bf16 v[52:55], v[42:45], v[2:5], 0
	v_mfma_f32_16x16x32_bf16 v[26:29], v[22:25], v[6:9], v[26:29]
	v_mfma_f32_16x16x32_bf16 v[18:21], v[22:25], v[14:17], v[18:21]
	v_mfma_f32_16x16x32_bf16 v[22:25], v[34:37], v[6:9], v[38:41]
	v_mfma_f32_16x16x32_bf16 v[34:37], v[34:37], v[14:17], v[30:33]
	s_nop 4
	v_mul_f32_e32 v38, 0x3fb8aa3b, v28
	v_mul_f32_e32 v39, 0x3fb8aa3b, v29
	v_and_b32_e32 v31, 64, v191
	v_xor_b32_e32 v30, 16, v191
	v_add_u32_e32 v31, 64, v31
	v_mfma_f32_16x16x32_bf16 v[42:45], v[42:45], v[10:13], 0
	v_cmp_lt_i32_e32 vcc, v30, v31
	v_mul_f32_e32 v33, 0x3fb8aa3b, v27
	v_xor_b32_e32 v32, 32, v191
	s_waitcnt lgkmcnt(1)
	v_mfma_f32_16x16x32_bf16 v[64:67], v[56:59], v[2:5], 0
	v_cndmask_b32_e32 v30, v191, v30, vcc
	v_lshlrev_b32_e32 v153, 2, v30
	v_mul_f32_e32 v30, 0x3fb8aa3b, v26
	v_mfma_f32_16x16x32_bf16 v[68:71], v[46:49], v[6:9], v[52:55]
	v_max3_f32 v30, v30, s51, v33
	v_max3_f32 v30, v30, v38, v39
	v_cmp_lt_i32_e32 vcc, v32, v31
	v_mfma_f32_16x16x32_bf16 v[40:43], v[46:49], v[14:17], v[42:45]
	v_mul_f32_e32 v48, 0x3fb8aa3b, v22
	v_mul_f32_e32 v49, 0x3fb8aa3b, v23
	v_mul_f32_e32 v52, 0x3fb8aa3b, v24
	s_waitcnt lgkmcnt(0)
	v_mfma_f32_16x16x32_bf16 v[44:47], v[60:63], v[6:9], v[64:67]
	v_mul_f32_e32 v53, 0x3fb8aa3b, v25
	v_max3_f32 v30, v30, v48, v49
	v_mul_f32_e32 v54, 0x3fb8aa3b, v68
	v_max3_f32 v30, v30, v52, v53
	v_mul_f32_e32 v33, 0x3fb8aa3b, v69
	v_max3_f32 v30, v30, v54, v33
	v_mul_f32_e32 v33, 0x3fb8aa3b, v70
	v_mul_f32_e32 v38, 0x3fb8aa3b, v71
	v_max3_f32 v30, v30, v33, v38
	v_mul_f32_e32 v33, 0x3fb8aa3b, v44
	v_mul_f32_e32 v38, 0x3fb8aa3b, v45
	v_max3_f32 v30, v30, v33, v38
	v_mul_f32_e32 v33, 0x3fb8aa3b, v46
	v_mul_f32_e32 v38, 0x3fb8aa3b, v47
	v_max3_f32 v38, v30, v33, v38
	ds_bpermute_b32 v39, v153, v38
	v_cndmask_b32_e32 v30, v191, v32, vcc
	v_lshlrev_b32_e32 v155, 2, v30
	v_mfma_f32_16x16x32_bf16 v[30:33], v[56:59], v[10:13], 0
	s_waitcnt lgkmcnt(0)
	v_max_f32_e32 v39, v39, v39
	v_max_f32_e32 v38, v38, v39
	ds_bpermute_b32 v39, v155, v38
	v_mfma_f32_16x16x32_bf16 v[72:75], v[60:63], v[14:17], v[30:33]
	s_waitcnt lgkmcnt(0)
	v_max3_f32 v157, v38, v39, s51
	v_fma_f32 v22, v22, s50, -v157
	v_exp_f32_e32 v60, v22
	v_fma_f32 v22, v23, s50, -v157
	v_exp_f32_e32 v64, v22
	v_fma_f32 v22, v24, s50, -v157
	v_exp_f32_e32 v54, v22
	v_fma_f32 v22, v25, s50, -v157
	v_exp_f32_e32 v58, v22
	v_fma_f32 v22, v68, s50, -v157
	v_exp_f32_e32 v62, v22
	v_fma_f32 v22, v69, s50, -v157
	v_exp_f32_e32 v66, v22
	v_fma_f32 v22, v70, s50, -v157
	v_exp_f32_e32 v68, v22
	v_fma_f32 v22, v71, s50, -v157
	v_exp_f32_e32 v70, v22
	v_mul_f32_e32 v22, 0x3fb8aa3b, v18
	v_mul_f32_e32 v23, 0x3fb8aa3b, v19
	v_max3_f32 v22, v22, s51, v23
	v_mul_f32_e32 v23, 0x3fb8aa3b, v20
	v_mul_f32_e32 v24, 0x3fb8aa3b, v21
	v_max3_f32 v22, v22, v23, v24
	v_mul_f32_e32 v23, 0x3fb8aa3b, v34
	v_mul_f32_e32 v24, 0x3fb8aa3b, v35
	v_max3_f32 v22, v22, v23, v24
	v_mul_f32_e32 v23, 0x3fb8aa3b, v36
	v_mul_f32_e32 v24, 0x3fb8aa3b, v37
	v_max3_f32 v22, v22, v23, v24
	v_mul_f32_e32 v23, 0x3fb8aa3b, v40
	v_mul_f32_e32 v24, 0x3fb8aa3b, v41
	v_max3_f32 v22, v22, v23, v24
	v_mul_f32_e32 v23, 0x3fb8aa3b, v42
	v_mul_f32_e32 v24, 0x3fb8aa3b, v43
	v_max3_f32 v22, v22, v23, v24
	v_mul_f32_e32 v23, 0x3fb8aa3b, v72
	v_mul_f32_e32 v24, 0x3fb8aa3b, v73
	v_max3_f32 v22, v22, v23, v24
	v_mul_f32_e32 v23, 0x3fb8aa3b, v74
	v_mul_f32_e32 v24, 0x3fb8aa3b, v75
	v_max3_f32 v22, v22, v23, v24
	ds_bpermute_b32 v23, v153, v22
	v_sub_f32_e32 v30, 0xf149f2ca, v157
	v_fma_f32 v26, v26, s50, -v157
	v_exp_f32_e32 v52, v30
	v_exp_f32_e32 v30, v26
	s_waitcnt lgkmcnt(0)
	v_max_f32_e32 v23, v23, v23
	v_max_f32_e32 v22, v22, v23
	ds_bpermute_b32 v23, v155, v22
	v_fma_f32 v26, v27, s50, -v157
	v_fma_f32 v24, v44, s50, -v157
	v_exp_f32_e32 v32, v26
	v_fma_f32 v26, v28, s50, -v157
	s_waitcnt lgkmcnt(0)
	v_max3_f32 v159, v22, v23, s51
	v_fma_f32 v18, v18, s50, -v159
	v_exp_f32_e32 v31, v18
	v_fma_f32 v18, v19, s50, -v159
	v_exp_f32_e32 v33, v18
	v_fma_f32 v18, v20, s50, -v159
	v_exp_f32_e32 v39, v18
	v_fma_f32 v18, v21, s50, -v159
	v_exp_f32_e32 v57, v18
	v_fma_f32 v18, v34, s50, -v159
	v_exp_f32_e32 v61, v18
	v_fma_f32 v18, v35, s50, -v159
	v_exp_f32_e32 v65, v18
	v_fma_f32 v18, v36, s50, -v159
	v_exp_f32_e32 v55, v18
	v_fma_f32 v18, v37, s50, -v159
	v_exp_f32_e32 v59, v18
	v_fma_f32 v18, v40, s50, -v159
	v_exp_f32_e32 v63, v18
	v_fma_f32 v18, v41, s50, -v159
	v_exp_f32_e32 v67, v18
	v_fma_f32 v18, v42, s50, -v159
	v_exp_f32_e32 v69, v18
	v_fma_f32 v18, v43, s50, -v159
	v_exp_f32_e32 v71, v18
	v_fma_f32 v18, v72, s50, -v159
	v_exp_f32_e32 v178, v24
	v_fma_f32 v24, v45, s50, -v157
	v_sub_f32_e32 v22, 0xf149f2ca, v159
	v_exp_f32_e32 v179, v18
	v_fma_f32 v18, v73, s50, -v159
	v_exp_f32_e32 v38, v26
	v_fma_f32 v26, v29, s50, -v157
	v_exp_f32_e32 v208, v24
	v_fma_f32 v24, v46, s50, -v157
	v_exp_f32_e32 v53, v22
	v_exp_f32_e32 v209, v18
	v_fma_f32 v18, v74, s50, -v159
	v_exp_f32_e32 v56, v26
	v_exp_f32_e32 v210, v24
	v_fma_f32 v24, v47, s50, -v157
	v_exp_f32_e32 v211, v18
	v_fma_f32 v18, v75, s50, -v159
	v_add_u32_e32 v22, 0x2000, v109
	v_exp_f32_e32 v212, v24
	v_exp_f32_e32 v213, v18
	ds_read2_b64 v[18:21], v22 offset0:128 offset1:132
	ds_read2_b64 v[22:25], v22 offset0:136 offset1:140
	v_pk_mul_f32 v[86:87], v[52:53], 0 op_sel_hi:[1,0]
	v_cvt_pk_bf16_f32 v78, v30, v32
	v_cvt_pk_bf16_f32 v79, v38, v56
	v_cvt_pk_bf16_f32 v80, v60, v64
	v_cvt_pk_bf16_f32 v82, v31, v33
	v_cvt_pk_bf16_f32 v83, v39, v57
	v_cvt_pk_bf16_f32 v84, v61, v65
	v_mov_b32_e32 v90, v86
	v_mov_b32_e32 v91, v86
	v_mov_b32_e32 v92, v86
	v_mov_b32_e32 v93, v86
	v_cvt_pk_bf16_f32 v81, v54, v58
	v_mov_b32_e32 v86, v87
	v_mov_b32_e32 v88, v87
	v_mov_b32_e32 v89, v87
	v_cvt_pk_bf16_f32 v85, v55, v59
	s_waitcnt lgkmcnt(1)
	v_mfma_f32_16x16x32_bf16 v[26:29], v[18:21], v[78:81], v[90:93]
	v_add_u32_e32 v34, 0x2800, v109
	v_cvt_pk_bf16_f32 v174, v62, v66
	v_cvt_pk_bf16_f32 v175, v68, v70
	v_mfma_f32_16x16x32_bf16 v[18:21], v[18:21], v[82:85], v[86:89]
	v_cvt_pk_bf16_f32 v176, v178, v208
	v_cvt_pk_bf16_f32 v177, v210, v212
	v_cvt_pk_bf16_f32 v192, v63, v67
	v_cvt_pk_bf16_f32 v193, v69, v71
	v_cvt_pk_bf16_f32 v194, v179, v209
	v_cvt_pk_bf16_f32 v195, v211, v213
	s_waitcnt lgkmcnt(0)
	v_mfma_f32_16x16x32_bf16 v[42:45], v[22:25], v[174:177], v[26:29]
	v_add_u32_e32 v40, 0x3000, v109
	ds_read2_b64 v[196:199], v40 offset0:192 offset1:196
	v_pk_add_f32 v[30:31], v[30:31], 0 op_sel_hi:[1,0]
	v_mfma_f32_16x16x32_bf16 v[18:21], v[22:25], v[192:195], v[18:21]
	ds_read2_b64 v[22:25], v34 offset0:160 offset1:164
	ds_read2_b64 v[34:37], v34 offset0:168 offset1:172
	v_pk_add_f32 v[30:31], v[32:33], v[30:31]
	s_waitcnt lgkmcnt(1)
	v_mfma_f32_16x16x32_bf16 v[26:29], v[22:25], v[78:81], v[90:93]
	v_add_f32_e64 v30, v38, v30
	v_add_f32_e64 v31, v39, v31
	v_pk_add_f32 v[30:31], v[56:57], v[30:31]
	s_waitcnt lgkmcnt(0)
	v_mfma_f32_16x16x32_bf16 v[46:49], v[34:37], v[174:177], v[26:29]
	v_add_f32_e64 v30, v60, v30
	v_add_f32_e64 v31, v61, v31
	v_pk_add_f32 v[56:57], v[64:65], v[30:31]
	v_add_co_u32_e32 v26, vcc, s48, v50
	v_mfma_f32_16x16x32_bf16 v[22:25], v[22:25], v[82:85], v[86:89]
	s_nop 0
	v_addc_co_u32_e32 v27, vcc, 0, v51, vcc
	v_add_co_u32_e32 v28, vcc, s49, v50
	v_mfma_f32_16x16x32_bf16 v[22:25], v[34:37], v[192:195], v[22:25]
	s_nop 0
	v_addc_co_u32_e32 v29, vcc, 0, v51, vcc
	global_load_dwordx4 v[94:97], v[26:27], off
	global_load_dwordx4 v[98:101], v[28:29], off
	global_load_dwordx4 v[102:105], v[170:171], off offset:256
	global_load_dwordx4 v[74:77], v[172:173], off offset:256
	ds_read2_b64 v[200:203], v40 offset0:200 offset1:204
	v_add_u32_e32 v40, 0x3800, v109
	v_mfma_f32_16x16x32_bf16 v[26:29], v[196:199], v[78:81], v[90:93]
	ds_read2_b64 v[204:207], v40 offset0:224 offset1:228
	v_pk_add_f32 v[54:55], v[54:55], v[56:57]
	v_mfma_f32_16x16x32_bf16 v[196:199], v[196:199], v[82:85], v[86:89]
	v_add_f32_e64 v54, v58, v54
	v_add_f32_e64 v55, v59, v55
	v_pk_add_f32 v[54:55], v[62:63], v[54:55]
	s_waitcnt lgkmcnt(1)
	v_mfma_f32_16x16x32_bf16 v[34:37], v[200:203], v[174:177], v[26:29]
	v_add_f32_e64 v54, v66, v54
	v_add_f32_e64 v55, v67, v55
	v_pk_add_f32 v[54:55], v[68:69], v[54:55]
	v_mfma_f32_16x16x32_bf16 v[26:29], v[200:203], v[192:195], v[196:199]
	v_add_f32_e64 v54, v70, v54
	v_add_f32_e64 v55, v71, v55
	v_pk_add_f32 v[54:55], v[178:179], v[54:55]
	ds_read2_b64 v[196:199], v40 offset0:232 offset1:236
	s_waitcnt lgkmcnt(1)
	v_mfma_f32_16x16x32_bf16 v[78:81], v[204:207], v[78:81], v[90:93]
	v_add_f32_e64 v54, v208, v54
	v_add_f32_e64 v55, v209, v55
	v_lshl_add_u64 v[178:179], v[50:51], 0, s[18:19]
	v_pk_add_f32 v[54:55], v[210:211], v[54:55]
	v_mfma_f32_16x16x32_bf16 v[82:85], v[204:207], v[82:85], v[86:89]
	v_add_f32_e64 v54, v212, v54
	v_add_f32_e64 v55, v213, v55
	s_waitcnt lgkmcnt(0)
	s_barrier
	v_mfma_f32_16x16x32_bf16 v[38:41], v[196:199], v[174:177], v[78:81]
	v_fma_f32 v174, v52, 0, v54
	v_fma_f32 v175, v53, 0, v55
	v_lshl_add_u64 v[176:177], v[50:51], 0, s[16:17]
	v_mfma_f32_16x16x32_bf16 v[30:33], v[196:199], v[192:195], v[82:85]
